# loop-edge edit: attention main-loop back edge rotated in front of the loop-back barrier; no-rescale path branches straight to the head
# speedup vs baseline: 1.0212x; 1.0036x over previous
.LBB0_830:
	v_lshlrev_b32_e32 v0, 1, v204
	v_lshrrev_b32_e32 v2, 2, v204
	v_and_b32_e32 v209, 32, v0
	v_lshlrev_b32_e32 v211, 3, v204
	v_and_or_b32 v2, v2, 3, v212
	v_add_u32_e32 v0, 0, v209
	v_and_b32_e32 v210, 24, v211
	v_lshlrev_b32_e32 v208, 6, v2
	v_add3_u32 v217, v0, v210, v208
	v_max3_f32 v0, v48, v49, v32
	v_max3_f32 v2, v50, v51, v33
	s_add_i32 s6, s83, s93
	v_max3_f32 v0, v0, v34, v35
	v_max3_f32 v2, v2, v54, v55
	s_add_i32 s1, s13, 0x100
	v_max3_f32 v0, v0, v52, v53
	v_max3_f32 v2, v2, v38, v39
	s_lshr_b32 s1, s1, 6
	v_max3_f32 v0, v0, v36, v37
	v_max3_f32 v2, v2, v58, v59
	v_lshl_add_u32 v207, v212, 2, s87
	v_max3_f32 v0, v0, v56, v57
	v_max3_f32 v2, v2, v42, v43
	s_mov_b32 s10, 1
	v_max3_f32 v0, v0, v40, v41
	v_max3_f32 v2, v2, v62, v63
	s_mov_b32 s23, 0
	v_max3_f32 v0, v0, v60, v61
	v_max3_f32 v2, v2, v46, v47
	s_andn2_b64 vcc, exec, s[4:5]
	v_max3_f32 v0, v0, v44, v45
	v_cmp_gt_u32_e64 s[4:5], 32, v204
	v_max_f32_e32 v0, v0, v2
	s_nop 0
	v_mov_b32_e32 v2, v0
	s_nop 1
	v_permlane32_swap_b32_e32 v0, v2
	v_max_f32_e32 v0, v0, v2
	s_nop 0
	v_add_f32_e32 v215, v1, v0
	v_sub_f32_e32 v2, v48, v0
	v_sub_f32_e32 v3, v32, v0
	v_sub_f32_e32 v4, v49, v0
	v_sub_f32_e32 v5, v33, v0
	v_sub_f32_e32 v6, v50, v0
	s_nop 0
	v_xor_b32_e32 v64, 0x80000000, v215
	v_mov_b32_e32 v65, v64
	v_mov_b32_e32 v66, v64
	v_mov_b32_e32 v67, v64
	v_mov_b32_e32 v68, v64
	v_mov_b32_e32 v69, v64
	v_mov_b32_e32 v70, v64
	v_mov_b32_e32 v71, v64
	v_mov_b32_e32 v72, v64
	v_mov_b32_e32 v73, v64
	v_mov_b32_e32 v74, v64
	v_mov_b32_e32 v75, v64
	v_mov_b32_e32 v76, v64
	v_mov_b32_e32 v77, v64
	v_mov_b32_e32 v78, v64
	v_mov_b32_e32 v79, v64
	s_waitcnt vmcnt(0) lgkmcnt(0)
	s_barrier
	s_mov_b32 m0, s6
	s_nop 0
	global_load_lds_dwordx4 v216, s[38:39]
	s_add_i32 s6, s84, s93
	s_mov_b32 m0, s6
	s_nop 0
	global_load_lds_dwordx4 v216, s[40:41]
	s_add_i32 s6, s78, 0xe000
	s_mov_b32 m0, s6
	s_nop 0
	global_load_lds_dwordx4 v216, s[42:43]
	ds_read_b128 v[196:199], v214 offset:12288
	ds_read_b128 v[184:187], v214 offset:12800
	ds_read_b128 v[188:191], v214 offset:14336
	ds_read_b128 v[192:195], v214 offset:14848
	v_sub_f32_e32 v7, v34, v0
	v_sub_f32_e32 v8, v51, v0
	v_sub_f32_e32 v9, v35, v0
	v_sub_f32_e32 v10, v52, v0
	v_sub_f32_e32 v11, v36, v0
	v_sub_f32_e32 v12, v53, v0
	v_sub_f32_e32 v13, v37, v0
	v_sub_f32_e32 v14, v54, v0
	v_sub_f32_e32 v15, v38, v0
	v_sub_f32_e32 v32, v55, v0
	v_sub_f32_e32 v33, v39, v0
	v_sub_f32_e32 v34, v56, v0
	v_sub_f32_e32 v35, v40, v0
	v_sub_f32_e32 v36, v57, v0
	v_sub_f32_e32 v37, v41, v0
	v_sub_f32_e32 v38, v58, v0
	v_sub_f32_e32 v39, v42, v0
	v_sub_f32_e32 v40, v59, v0
	v_sub_f32_e32 v41, v43, v0
	v_sub_f32_e32 v42, v60, v0
	v_sub_f32_e32 v43, v44, v0
	v_sub_f32_e32 v44, v61, v0
	v_sub_f32_e32 v45, v45, v0
	v_sub_f32_e32 v48, v62, v0
	v_sub_f32_e32 v46, v46, v0
	v_sub_f32_e32 v49, v63, v0
	v_sub_f32_e32 v0, v47, v0
	v_exp_f32_e32 v96, v2
	v_exp_f32_e32 v97, v4
	v_exp_f32_e32 v98, v6
	v_exp_f32_e32 v99, v8
	v_exp_f32_e32 v100, v10
	v_exp_f32_e32 v101, v12
	v_exp_f32_e32 v102, v14
	v_exp_f32_e32 v103, v32
	v_exp_f32_e32 v104, v34
	v_exp_f32_e32 v105, v36
	v_exp_f32_e32 v106, v38
	v_exp_f32_e32 v107, v40
	v_exp_f32_e32 v108, v42
	v_exp_f32_e32 v109, v44
	v_exp_f32_e32 v110, v48
	v_exp_f32_e32 v111, v49
	v_exp_f32_e32 v80, v3
	v_exp_f32_e32 v81, v5
	v_exp_f32_e32 v82, v7
	v_exp_f32_e32 v83, v9
	v_exp_f32_e32 v84, v11
	v_exp_f32_e32 v85, v13
	v_exp_f32_e32 v86, v15
	v_exp_f32_e32 v87, v33
	v_exp_f32_e32 v88, v35
	v_exp_f32_e32 v89, v37
	v_exp_f32_e32 v90, v39
	v_exp_f32_e32 v91, v41
	v_exp_f32_e32 v92, v43
	v_exp_f32_e32 v93, v45
	v_exp_f32_e32 v94, v46
	v_exp_f32_e32 v95, v0
	s_cbranch_vccnz .LBB0_846
	v_mov_b32_e32 v14, v1
	v_mov_b32_e32 v15, v1
	v_mov_b32_e32 v0, v1
	v_mov_b32_e32 v2, v1
	v_mov_b32_e32 v3, v1
	v_mov_b32_e32 v4, v1
	v_mov_b32_e32 v5, v1
	v_mov_b32_e32 v6, v1
	v_mov_b32_e32 v7, v1
	v_mov_b32_e32 v8, v1
	v_mov_b32_e32 v9, v1
	v_mov_b32_e32 v10, v1
	v_mov_b32_e32 v11, v1
	v_mov_b32_e32 v12, v1
	v_mov_b32_e32 v13, v1
	v_mov_b64_e32 v[62:63], v[14:15]
	v_mov_b64_e32 v[46:47], v[14:15]
	s_add_i32 s66, s1, -5
	v_lshl_add_u32 v219, v205, 2, s87
	s_mov_b32 s62, 0
	s_mov_b32 s101, 0
	s_movk_i32 s23, 0x4000
	s_movk_i32 s10, 0x2000
	v_mov_b32_e32 v218, 0
	s_mov_b32 s67, 4
	s_mov_b64 s[6:7], s[52:53]
	s_mov_b64 s[58:59], s[50:51]
	s_mov_b64 s[60:61], s[48:49]
	v_mov_b64_e32 v[60:61], v[12:13]
	v_mov_b64_e32 v[58:59], v[10:11]
	v_mov_b64_e32 v[56:57], v[8:9]
	v_mov_b64_e32 v[54:55], v[6:7]
	v_mov_b64_e32 v[52:53], v[4:5]
	v_mov_b64_e32 v[50:51], v[2:3]
	v_mov_b64_e32 v[48:49], v[0:1]
	v_mov_b64_e32 v[44:45], v[12:13]
	v_mov_b64_e32 v[42:43], v[10:11]
	v_mov_b64_e32 v[40:41], v[8:9]
	v_mov_b64_e32 v[38:39], v[6:7]
	v_mov_b64_e32 v[36:37], v[4:5]
	v_mov_b64_e32 v[34:35], v[2:3]
	v_mov_b64_e32 v[32:33], v[0:1]
.LBB0_832:
	v_cvt_pk_bf16_f32 v172, v104, v105
	v_cvt_pk_bf16_f32 v180, v96, v97
	s_add_i32 s12, s67, -3
	s_and_b32 s22, s12, 3
	s_mulk_i32 s22, 0x3000
	v_add_u32_e32 v0, s22, v214
	ds_read_b128 v[2:5], v0 offset:4096
	v_add_u32_e32 v14, s101, v217
	s_waitcnt lgkmcnt(4)
	v_mfma_f32_32x32x16_bf16 v[128:143], v[196:199], v[176:179], v[64:79]
	v_add_f32_e32 v6, v96, v97
	v_add_f32_e32 v6, v98, v6
	v_add_f32_e32 v6, v99, v6
	v_add_f32_e32 v10, v100, v6
	ds_read_b128 v[6:9], v0 offset:4608
	s_waitcnt lgkmcnt(4)
	v_mfma_f32_32x32x16_bf16 v[112:127], v[184:187], v[176:179], v[64:79]
	v_add_f32_e32 v10, v101, v10
	v_add_f32_e32 v10, v102, v10
	v_add_f32_e32 v15, v103, v10
	v_cvt_pk_bf16_f32 v181, v98, v99
	s_add_u32 s62, s58, 0xffff0000
	s_addc_u32 s63, s59, -1
	s_and_b32 s12, s67, 3
	s_mulk_i32 s12, 0x3000
	s_add_i32 s64, s12, s78
	s_mov_b32 m0, s64
	s_nop 0
	global_load_lds_dwordx4 v216, s[62:63]
	ds_read_b128 v[10:13], v0 offset:6144
	s_waitcnt lgkmcnt(4)
	v_mfma_f32_32x32x16_bf16 v[128:143], v[188:191], v[168:171], v[128:143]
	v_add_f32_e32 v15, v104, v15
	v_add_f32_e32 v15, v105, v15
	v_add_f32_e32 v15, v106, v15
	v_cvt_pk_bf16_f32 v182, v100, v101
	ds_read_b128 v[96:99], v0 offset:6656
	s_waitcnt lgkmcnt(4)
	v_mfma_f32_32x32x16_bf16 v[112:127], v[192:195], v[168:171], v[112:127]
	v_add_f32_e32 v15, v107, v15
	v_add_f32_e32 v15, v108, v15
	v_add_f32_e32 v15, v109, v15
	v_cvt_pk_bf16_f32 v183, v102, v103
	s_add_u32 s62, s60, 0xfffff000
	s_addc_u32 s63, s61, -1
	s_add_i32 s12, s12, s85
	s_mov_b32 m0, s12
	s_nop 0
	global_load_lds_dwordx4 v216, s[62:63]
	ds_read_b128 v[100:103], v0 offset:8192
	s_waitcnt lgkmcnt(4)
	v_mfma_f32_32x32x16_bf16 v[128:143], v[2:5], v[164:167], v[128:143]
	v_add_f32_e32 v15, v110, v15
	v_add_f32_e32 v15, v111, v15
	v_add_f32_e32 v15, v80, v15
	ds_read_b128 v[2:5], v0 offset:8704
	s_waitcnt lgkmcnt(4)
	v_mfma_f32_32x32x16_bf16 v[112:127], v[6:9], v[164:167], v[112:127]
	v_add_f32_e32 v15, v81, v15
	v_add_f32_e32 v15, v82, v15
	v_add_f32_e32 v15, v83, v15
	v_cvt_pk_bf16_f32 v173, v106, v107
	s_add_u32 s62, s6, 0xffff0000
	s_addc_u32 s63, s7, -1
	s_add_i32 s12, s23, s86
	s_mov_b32 m0, s12
	s_nop 0
	global_load_lds_dwordx4 v216, s[62:63]
	ds_read_b128 v[104:107], v0 offset:10240
	s_waitcnt lgkmcnt(4)
	v_mfma_f32_32x32x16_bf16 v[128:143], v[10:13], v[156:159], v[128:143]
	v_add_f32_e32 v6, v84, v15
	v_add_f32_e32 v6, v85, v6
	v_cvt_pk_bf16_f32 v174, v108, v109
	v_cvt_pk_bf16_f32 v175, v110, v111
	ds_read_b128 v[108:111], v0 offset:10752
	s_waitcnt lgkmcnt(4)
	v_mfma_f32_32x32x16_bf16 v[112:127], v[96:99], v[156:159], v[112:127]
	v_add_f32_e32 v0, v86, v6
	v_add_f32_e32 v0, v87, v0
	v_cvt_pk_bf16_f32 v160, v80, v81
	v_cvt_pk_bf16_f32 v161, v82, v83
	ds_read_b64_tr_b16 v[6:7], v14 offset:49152
	ds_read_b64_tr_b16 v[8:9], v14 offset:49664
	s_waitcnt lgkmcnt(5)
	v_mfma_f32_32x32x16_bf16 v[128:143], v[100:103], v[148:151], v[128:143]
	v_add_f32_e32 v0, v88, v0
	v_add_f32_e32 v0, v89, v0
	v_cvt_pk_bf16_f32 v162, v84, v85
	v_cvt_pk_bf16_f32 v163, v86, v87
	ds_read_b64_tr_b16 v[10:11], v14 offset:53248
	ds_read_b64_tr_b16 v[12:13], v14 offset:53760
	s_waitcnt lgkmcnt(6)
	v_mfma_f32_32x32x16_bf16 v[112:127], v[2:5], v[148:151], v[112:127]
	v_add_f32_e32 v0, v90, v0
	v_add_f32_e32 v0, v91, v0
	v_cvt_pk_bf16_f32 v152, v88, v89
	v_cvt_pk_bf16_f32 v153, v90, v91
	ds_read_b64_tr_b16 v[80:81], v14 offset:50176
	ds_read_b64_tr_b16 v[82:83], v14 offset:50688
	s_waitcnt lgkmcnt(7)
	v_mfma_f32_32x32x16_bf16 v[128:143], v[104:107], v[144:147], v[128:143]
	v_add_f32_e32 v0, v92, v0
	v_add_f32_e32 v0, v93, v0
	v_cvt_pk_bf16_f32 v154, v92, v93
	ds_read_b64_tr_b16 v[2:3], v14 offset:54272
	ds_read_b64_tr_b16 v[4:5], v14 offset:54784
	s_waitcnt lgkmcnt(8)
	v_mfma_f32_32x32x16_bf16 v[112:127], v[108:111], v[144:147], v[112:127]
	v_add_f32_e32 v0, v94, v0
	v_add_f32_e32 v0, v95, v0
	v_cvt_pk_bf16_f32 v155, v94, v95
	s_nop 1
	v_max_f32_e32 v15, v128, v129
	s_add_i32 s12, s67, -2
	s_and_b32 s12, s12, 3
	s_mulk_i32 s12, 0x3000
	s_nop 2
	v_max3_f32 v84, v130, v131, v113
	v_max3_f32 v15, v15, v112, v114
	v_max3_f32 v15, v15, v115, v132
	v_max3_f32 v84, v84, v134, v135
	v_max3_f32 v15, v15, v133, v116
	v_max3_f32 v84, v84, v118, v119
	v_max3_f32 v15, v15, v117, v136
	v_max3_f32 v84, v84, v138, v139
	v_max3_f32 v15, v15, v137, v120
	v_max3_f32 v84, v84, v122, v123
	v_max3_f32 v15, v15, v121, v140
	v_max3_f32 v84, v84, v142, v143
	v_max3_f32 v15, v15, v141, v124
	v_max3_f32 v84, v84, v126, v127
	v_max3_f32 v15, v15, v125, v84
	v_mov_b32_e32 v84, v15
	s_nop 1
	v_permlane32_swap_b32_e32 v15, v84
	v_max_f32_e32 v15, v15, v84
	v_cmp_lt_f32_e32 vcc, s94, v15
	s_cmp_lg_u64 vcc, 0
	v_add_f32_e32 v0, v218, v0
	s_cselect_b64 s[62:63], -1, 0
	s_cbranch_vccnz .LBB0_840

.LBB0_836:
	s_waitcnt lgkmcnt(6)
	v_mfma_f32_32x32x16_bf16 v[48:63], v[180:183], v[112:115], v[48:63]
	v_exp_f32_e32 v96, v96
	v_exp_f32_e32 v97, v97
	v_exp_f32_e32 v98, v98
	v_exp_f32_e32 v99, v99
	ds_read_b64_tr_b16 v[112:113], v14 offset:51200
	ds_read_b64_tr_b16 v[114:115], v14 offset:51712
	s_waitcnt lgkmcnt(6)
	v_mfma_f32_32x32x16_bf16 v[32:47], v[180:183], v[10:13], v[32:47]
	v_exp_f32_e32 v100, v100
	v_exp_f32_e32 v101, v101
	v_exp_f32_e32 v102, v102
	v_exp_f32_e32 v103, v103
	ds_read_b64_tr_b16 v[10:11], v14 offset:55296
	ds_read_b64_tr_b16 v[12:13], v14 offset:55808
	s_waitcnt lgkmcnt(6)
	v_mfma_f32_32x32x16_bf16 v[48:63], v[172:175], v[6:9], v[48:63]
	v_exp_f32_e32 v104, v104
	v_exp_f32_e32 v105, v105
	v_exp_f32_e32 v106, v106
	v_exp_f32_e32 v107, v107
	ds_read_b64_tr_b16 v[6:7], v14 offset:52224
	ds_read_b64_tr_b16 v[8:9], v14 offset:52736
	s_waitcnt lgkmcnt(6)
	v_mfma_f32_32x32x16_bf16 v[32:47], v[172:175], v[2:5], v[32:47]
	v_exp_f32_e32 v108, v108
	v_exp_f32_e32 v109, v109
	v_exp_f32_e32 v110, v110
	v_exp_f32_e32 v111, v111
	v_add_u32_e32 v0, s22, v214
	ds_read_b64_tr_b16 v[2:3], v14 offset:56320
	ds_read_b64_tr_b16 v[4:5], v14 offset:56832
	ds_read_b128 v[196:199], v0
	s_waitcnt lgkmcnt(7)
	v_mfma_f32_32x32x16_bf16 v[48:63], v[160:163], v[112:115], v[48:63]
	v_exp_f32_e32 v80, v80
	v_exp_f32_e32 v81, v81
	v_exp_f32_e32 v82, v82
	v_exp_f32_e32 v83, v83
	ds_read_b128 v[184:187], v0 offset:512
	s_waitcnt lgkmcnt(6)
	v_mfma_f32_32x32x16_bf16 v[32:47], v[160:163], v[10:13], v[32:47]
	v_exp_f32_e32 v84, v84
	v_exp_f32_e32 v85, v85
	v_exp_f32_e32 v86, v86
	v_exp_f32_e32 v87, v87
	ds_read_b128 v[188:191], v0 offset:2048
	s_waitcnt lgkmcnt(5)
	v_mfma_f32_32x32x16_bf16 v[48:63], v[152:155], v[6:9], v[48:63]
	v_exp_f32_e32 v88, v88
	v_exp_f32_e32 v89, v89
	v_exp_f32_e32 v90, v90
	v_exp_f32_e32 v91, v91
	ds_read_b128 v[192:195], v0 offset:2560
	s_waitcnt lgkmcnt(4)
	v_mfma_f32_32x32x16_bf16 v[32:47], v[152:155], v[2:5], v[32:47]
	v_exp_f32_e32 v92, v92
	v_exp_f32_e32 v93, v93
	v_exp_f32_e32 v94, v94
	v_exp_f32_e32 v95, v95
	s_add_i32 s22, s12, 0x2000
	s_cmpk_lg_i32 s12, 0x4000
	s_cselect_b32 s22, s22, 0
	s_add_u32 s60, s60, 0x2000
	s_addc_u32 s61, s61, 0
	s_add_u32 s58, s58, 0x20000
	s_addc_u32 s59, s59, 0
	s_add_i32 s67, s67, 2
	s_add_u32 s6, s6, 0x20000
	s_addc_u32 s7, s7, 0
	s_cmp_ge_i32 s10, s66
	s_cbranch_scc1 .Latt_mx
	s_mov_b32 s101, s23
	s_mov_b32 s10, s12
	s_mov_b32 s23, s22
	s_waitcnt vmcnt(3) lgkmcnt(0)
	s_barrier
	s_andn2_b64 vcc, exec, s[62:63]
	s_cbranch_vccnz .LBB0_832
	s_waitcnt lgkmcnt(0)
	ds_read_b128 v[2:5], v207 offset:96
	ds_read_b128 v[6:9], v207 offset:64
	ds_read_b128 v[10:13], v207 offset:32
	ds_read_b128 v[112:115], v207
	s_waitcnt lgkmcnt(3)
	v_pk_mul_f32 v[62:63], v[62:63], v[4:5]
	s_waitcnt lgkmcnt(2)
	v_pk_mul_f32 v[58:59], v[58:59], v[8:9]
	s_waitcnt lgkmcnt(1)
	v_pk_mul_f32 v[54:55], v[54:55], v[12:13]
	s_waitcnt lgkmcnt(0)
	v_pk_mul_f32 v[50:51], v[50:51], v[114:115]
	v_pk_mul_f32 v[60:61], v[60:61], v[2:3]
	v_pk_mul_f32 v[56:57], v[56:57], v[6:7]
	v_pk_mul_f32 v[52:53], v[52:53], v[10:11]
	v_pk_mul_f32 v[48:49], v[48:49], v[112:113]
	v_pk_mul_f32 v[46:47], v[46:47], v[4:5]
	v_pk_mul_f32 v[42:43], v[42:43], v[8:9]
	v_pk_mul_f32 v[38:39], v[38:39], v[12:13]
	v_pk_mul_f32 v[34:35], v[34:35], v[114:115]
	v_pk_mul_f32 v[44:45], v[44:45], v[2:3]
	v_pk_mul_f32 v[40:41], v[40:41], v[6:7]
	v_pk_mul_f32 v[36:37], v[36:37], v[10:11]
	v_pk_mul_f32 v[32:33], v[32:33], v[112:113]
	s_branch .LBB0_832
.Latt_mx:
	s_waitcnt vmcnt(3) lgkmcnt(0)
	s_barrier
	s_andn2_b64 vcc, exec, s[62:63]
	s_cbranch_vccnz .LBB0_847
	s_waitcnt lgkmcnt(0)
	ds_read_b128 v[2:5], v207 offset:96
	ds_read_b128 v[6:9], v207 offset:64
	ds_read_b128 v[10:13], v207 offset:32
	ds_read_b128 v[112:115], v207
	s_waitcnt lgkmcnt(3)
	v_pk_mul_f32 v[62:63], v[62:63], v[4:5]
	s_waitcnt lgkmcnt(2)
	v_pk_mul_f32 v[58:59], v[58:59], v[8:9]
	s_waitcnt lgkmcnt(1)
	v_pk_mul_f32 v[54:55], v[54:55], v[12:13]
	s_waitcnt lgkmcnt(0)
	v_pk_mul_f32 v[50:51], v[50:51], v[114:115]
	v_pk_mul_f32 v[60:61], v[60:61], v[2:3]
	v_pk_mul_f32 v[56:57], v[56:57], v[6:7]
	v_pk_mul_f32 v[52:53], v[52:53], v[10:11]
	v_pk_mul_f32 v[48:49], v[48:49], v[112:113]
	v_pk_mul_f32 v[46:47], v[46:47], v[4:5]
	v_pk_mul_f32 v[42:43], v[42:43], v[8:9]
	v_pk_mul_f32 v[38:39], v[38:39], v[12:13]
	v_pk_mul_f32 v[34:35], v[34:35], v[114:115]
	v_pk_mul_f32 v[44:45], v[44:45], v[2:3]
	v_pk_mul_f32 v[40:41], v[40:41], v[6:7]
	v_pk_mul_f32 v[36:37], v[36:37], v[10:11]
	v_pk_mul_f32 v[32:33], v[32:33], v[112:113]
	s_branch .LBB0_847
